# sa2 + in-projection GEMM K-loop LDS-DMA loads converted to SGPR-base addressing (16 per iteration)
# baseline (speedup 1.0000x reference)
; #define PG8_STAGE(bufoff, gbase, voff) do { _Pragma("unroll") for (int _i = 0; _i < 2; ++_i) \
;         __builtin_amdgcn_global_load_lds((const unsigned*)((const char*)(gbase) + (voff)[_i]), (PG8_LAS unsigned*)(lds + (bufoff) + ldsw + _i * 8192), 16, 0, 0); } while (0)
; #define PG8_LDA(dst, b, h) do { _Pragma("unroll") for (int m = 0; m < 4; ++m) _Pragma("unroll") for (int k = 0; k < 2; ++k) dst[m][k] = *(const PG8_LAS bf16x8*)(lds + PG8_SA(b, h) + aoff + m * 2048 + k * 1024); } while (0)
; #define PG8_LDB(dst, b, h) do { _Pragma("unroll") for (int n = 0; n < 2; ++n) _Pragma("unroll") for (int k = 0; k < 2; ++k) dst[n][k] = *(const PG8_LAS bf16x8*)(lds + PG8_SB(b, h) + boff + n * 2048 + k * 1024); } while (0)
; #define PG8_MMA(ai, bj, At, Bt) do { __builtin_amdgcn_s_setprio(1); _Pragma("unroll") for (int m = 0; m < 4; ++m) _Pragma("unroll") for (int n = 0; n < 2; ++n) _Pragma("unroll") for (int k = 0; k < 2; ++k) \
;         acc[ai][bj][m][n] = __builtin_amdgcn_mfma_f32_16x16x32_bf16(Bt[n][k], At[m][k], acc[ai][bj][m][n], 0, 0, 0); __builtin_amdgcn_s_setprio(0); } while (0)
; #define PG8_WAIT_V(n) asm volatile("s_waitcnt vmcnt(" #n ")" ::: "memory")
; template <class Epi, class Sched, bool ALIGN_EPI = false, bool SP2 = false>
; __device__ __forceinline__ void gemm_phase(PG8_LAS unsigned char* lds, const Gemm g, const Sched& S, const Epi& E) {
;     ...
;             PG8_LDB(B0, 0, 0); PG8_LDB(B1, 0, 1); PG8_SCHED; PG8_LDA(At, 0, 0); PG8_STAGE(PG8_SA(1, 1), a1 + hstep, voffA);
;             PG8_WAIT_V(8); PG8_WAIT_L(0); PG8_BAR; PG8_MMA(0, 0, At, B0); PG8_MMA(0, 1, At, B1); PG8_BAR; PG8_SCHED;
;             PG8_LDA(At, 0, 1); PG8_STAGE(PG8_SB(0, 0), b2, voffB); PG8_STAGE(PG8_SB(0, 1), b2 + hstep, voffB); PG8_STAGE(PG8_SA(0, 0), a2, voffA);
;             PG8_WAIT_V(8); PG8_WAIT_L(0); PG8_BAR; PG8_MMA(1, 0, At, B0); PG8_MMA(1, 1, At, B1); PG8_BAR; PG8_SCHED;
;             PG8_LDB(B0, 1, 0); PG8_LDB(B1, 1, 1); PG8_SCHED; PG8_LDA(At, 1, 0); PG8_STAGE(PG8_SA(0, 1), a2 + hstep, voffA);
;             PG8_WAIT_V(8); PG8_WAIT_L(0); PG8_BAR; PG8_MMA(0, 0, At, B0); PG8_MMA(0, 1, At, B1); PG8_BAR; PG8_SCHED;
;             PG8_LDA(At, 1, 1); PG8_STAGE(PG8_SB(1, 0), b3, voffB); PG8_STAGE(PG8_SB(1, 1), b3 + hstep, voffB); PG8_STAGE(PG8_SA(1, 0), a3, voffA);
;             PG8_WAIT_V(8); PG8_WAIT_L(0); PG8_BAR; PG8_MMA(1, 0, At, B0); PG8_MMA(1, 1, At, B1); PG8_BAR; PG8_SCHED;
.LBB0_142:
	ds_read_b128 v[130:133], v158
	ds_read_b128 v[152:155], v158 offset:1024
	ds_read_b128 v[162:165], v158 offset:2048
	ds_read_b128 v[166:169], v158 offset:3072
	ds_read_b128 v[170:173], v159
	ds_read_b128 v[174:177], v159 offset:1024
	ds_read_b128 v[178:181], v159 offset:2048
	ds_read_b128 v[182:185], v159 offset:3072
	s_add_u32 s40, s38, 0xfffc0080
	s_addc_u32 s41, s39, -1
	s_cmp_eq_u32 s48, 12
	s_cselect_b32 s45, s6, s41
	s_cselect_b32 s44, s29, s40
	s_cselect_b32 s41, s27, s47
	s_cselect_b32 s40, s43, s46
	s_add_i32 m0, s37, 0xc000
	ds_read_b128 v[186:189], v160
	ds_read_b128 v[190:193], v160 offset:1024
	ds_read_b128 v[198:201], v160 offset:2048
	ds_read_b128 v[202:205], v160 offset:3072
	ds_read_b128 v[206:209], v160 offset:4096
	ds_read_b128 v[210:213], v160 offset:5120
	ds_read_b128 v[214:217], v160 offset:6144
	ds_read_b128 v[218:221], v160 offset:7168
	global_load_lds_dwordx4 v144, s[38:39]
	s_add_i32 m0, s37, 0xe000
	s_nop 0
	global_load_lds_dwordx4 v146, s[38:39]
	s_waitcnt vmcnt(8)
	s_waitcnt lgkmcnt(0)
	s_barrier
	s_setprio 1
	s_waitcnt lgkmcnt(0)
	v_mfma_f32_16x16x32_bf16 v[126:129], v[130:133], v[186:189], v[126:129]
	v_mfma_f32_16x16x32_bf16 v[122:125], v[162:165], v[186:189], v[122:125]
	v_mfma_f32_16x16x32_bf16 v[114:117], v[130:133], v[198:201], v[114:117]
	v_mfma_f32_16x16x32_bf16 v[106:109], v[162:165], v[198:201], v[106:109]
	v_mfma_f32_16x16x32_bf16 v[98:101], v[130:133], v[206:209], v[98:101]
	v_mfma_f32_16x16x32_bf16 v[90:93], v[162:165], v[206:209], v[90:93]
	v_mfma_f32_16x16x32_bf16 v[82:85], v[130:133], v[214:217], v[82:85]
	v_mfma_f32_16x16x32_bf16 v[74:77], v[162:165], v[214:217], v[74:77]
	v_mfma_f32_16x16x32_bf16 v[126:129], v[152:155], v[190:193], v[126:129]
	v_mfma_f32_16x16x32_bf16 v[122:125], v[166:169], v[190:193], v[122:125]
	v_mfma_f32_16x16x32_bf16 v[114:117], v[152:155], v[202:205], v[114:117]
	v_mfma_f32_16x16x32_bf16 v[106:109], v[166:169], v[202:205], v[106:109]
	v_mfma_f32_16x16x32_bf16 v[98:101], v[152:155], v[210:213], v[98:101]
	v_mfma_f32_16x16x32_bf16 v[90:93], v[166:169], v[210:213], v[90:93]
	v_mfma_f32_16x16x32_bf16 v[82:85], v[152:155], v[218:221], v[82:85]
	v_mfma_f32_16x16x32_bf16 v[74:77], v[166:169], v[218:221], v[74:77]
	s_setprio 0
	s_setprio 1
	v_mfma_f32_16x16x32_bf16 v[118:121], v[170:173], v[186:189], v[118:121]
	v_mfma_f32_16x16x32_bf16 v[110:113], v[178:181], v[186:189], v[110:113]
	v_mfma_f32_16x16x32_bf16 v[102:105], v[170:173], v[198:201], v[102:105]
	v_mfma_f32_16x16x32_bf16 v[94:97], v[178:181], v[198:201], v[94:97]
	v_mfma_f32_16x16x32_bf16 v[86:89], v[170:173], v[206:209], v[86:89]
	v_mfma_f32_16x16x32_bf16 v[78:81], v[178:181], v[206:209], v[78:81]
	v_mfma_f32_16x16x32_bf16 v[70:73], v[170:173], v[214:217], v[70:73]
	v_mfma_f32_16x16x32_bf16 v[66:69], v[178:181], v[214:217], v[66:69]
	v_mfma_f32_16x16x32_bf16 v[118:121], v[174:177], v[190:193], v[118:121]
	v_mfma_f32_16x16x32_bf16 v[110:113], v[182:185], v[190:193], v[110:113]
	v_mfma_f32_16x16x32_bf16 v[102:105], v[174:177], v[202:205], v[102:105]
	v_mfma_f32_16x16x32_bf16 v[94:97], v[182:185], v[202:205], v[94:97]
	v_mfma_f32_16x16x32_bf16 v[86:89], v[174:177], v[210:213], v[86:89]
	v_mfma_f32_16x16x32_bf16 v[78:81], v[182:185], v[210:213], v[78:81]
	v_mfma_f32_16x16x32_bf16 v[70:73], v[174:177], v[218:221], v[70:73]
	v_mfma_f32_16x16x32_bf16 v[66:69], v[182:185], v[218:221], v[66:69]
	s_setprio 0
	s_barrier
	s_add_i32 s49, s60, s17
	s_add_u32 s98, s40, s10
	s_addc_u32 s99, s41, s11
	s_mov_b32 m0, s49
	ds_read_b128 v[186:189], v160 offset:16384
	ds_read_b128 v[190:193], v160 offset:17408
	ds_read_b128 v[198:201], v160 offset:18432
	ds_read_b128 v[202:205], v160 offset:19456
	ds_read_b128 v[206:209], v160 offset:20480
	ds_read_b128 v[210:213], v160 offset:21504
	ds_read_b128 v[214:217], v160 offset:22528
	ds_read_b128 v[218:221], v160 offset:23552
	global_load_lds_dwordx4 v136, s[40:41]
	s_add_i32 m0, s49, 0x2000
	s_add_u32 s50, s40, 0x40000
	s_addc_u32 s51, s41, 0
	s_add_i32 s49, s61, s17
	global_load_lds_dwordx4 v140, s[40:41]
	s_mov_b32 m0, s49
	s_add_u32 s100, s44, s10
	s_addc_u32 s101, s45, s11
	global_load_lds_dwordx4 v136, s[50:51]
	s_add_i32 m0, s49, 0x2000
	s_nop 0
	global_load_lds_dwordx4 v140, s[50:51]
	s_mov_b32 m0, s37
	s_nop 0
	global_load_lds_dwordx4 v134, s[44:45]
	s_mov_b32 m0, s52
	s_nop 0
	global_load_lds_dwordx4 v138, s[44:45]
	s_waitcnt vmcnt(8)
	s_waitcnt lgkmcnt(0)
	s_barrier
	s_setprio 1
	s_waitcnt lgkmcnt(0)
	v_mfma_f32_16x16x32_bf16 v[62:65], v[130:133], v[186:189], v[62:65]
	v_mfma_f32_16x16x32_bf16 v[58:61], v[162:165], v[186:189], v[58:61]
	v_mfma_f32_16x16x32_bf16 v[50:53], v[130:133], v[198:201], v[50:53]
	v_mfma_f32_16x16x32_bf16 v[42:45], v[162:165], v[198:201], v[42:45]
	v_mfma_f32_16x16x32_bf16 v[34:37], v[130:133], v[206:209], v[34:37]
	v_mfma_f32_16x16x32_bf16 v[26:29], v[162:165], v[206:209], v[26:29]
	v_mfma_f32_16x16x32_bf16 v[18:21], v[130:133], v[214:217], v[18:21]
	v_mfma_f32_16x16x32_bf16 v[10:13], v[162:165], v[214:217], v[10:13]
	v_mfma_f32_16x16x32_bf16 v[62:65], v[152:155], v[190:193], v[62:65]
	v_mfma_f32_16x16x32_bf16 v[58:61], v[166:169], v[190:193], v[58:61]
	v_mfma_f32_16x16x32_bf16 v[50:53], v[152:155], v[202:205], v[50:53]
	v_mfma_f32_16x16x32_bf16 v[42:45], v[166:169], v[202:205], v[42:45]
	v_mfma_f32_16x16x32_bf16 v[34:37], v[152:155], v[210:213], v[34:37]
	v_mfma_f32_16x16x32_bf16 v[26:29], v[166:169], v[210:213], v[26:29]
	v_mfma_f32_16x16x32_bf16 v[18:21], v[152:155], v[218:221], v[18:21]
	v_mfma_f32_16x16x32_bf16 v[10:13], v[166:169], v[218:221], v[10:13]
	s_setprio 0
	s_setprio 1
	v_mfma_f32_16x16x32_bf16 v[54:57], v[170:173], v[186:189], v[54:57]
	v_mfma_f32_16x16x32_bf16 v[46:49], v[178:181], v[186:189], v[46:49]
	v_mfma_f32_16x16x32_bf16 v[38:41], v[170:173], v[198:201], v[38:41]
	v_mfma_f32_16x16x32_bf16 v[30:33], v[178:181], v[198:201], v[30:33]
	v_mfma_f32_16x16x32_bf16 v[22:25], v[170:173], v[206:209], v[22:25]
	v_mfma_f32_16x16x32_bf16 v[14:17], v[178:181], v[206:209], v[14:17]
	v_mfma_f32_16x16x32_bf16 v[6:9], v[170:173], v[214:217], v[6:9]
	v_mfma_f32_16x16x32_bf16 v[2:5], v[178:181], v[214:217], v[2:5]
	v_mfma_f32_16x16x32_bf16 v[54:57], v[174:177], v[190:193], v[54:57]
	v_mfma_f32_16x16x32_bf16 v[46:49], v[182:185], v[190:193], v[46:49]
	v_mfma_f32_16x16x32_bf16 v[38:41], v[174:177], v[202:205], v[38:41]
	v_mfma_f32_16x16x32_bf16 v[30:33], v[182:185], v[202:205], v[30:33]
	v_mfma_f32_16x16x32_bf16 v[22:25], v[174:177], v[210:213], v[22:25]
	v_mfma_f32_16x16x32_bf16 v[14:17], v[182:185], v[210:213], v[14:17]
	v_mfma_f32_16x16x32_bf16 v[6:9], v[174:177], v[218:221], v[6:9]
	v_mfma_f32_16x16x32_bf16 v[2:5], v[182:185], v[218:221], v[2:5]
	s_setprio 0
	s_barrier
; #define PG8_STAGE(bufoff, gbase, voff) do { _Pragma("unroll") for (int _i = 0; _i < 2; ++_i) \
;         __builtin_amdgcn_global_load_lds((const unsigned*)((const char*)(gbase) + (voff)[_i]), (PG8_LAS unsigned*)(lds + (bufoff) + ldsw + _i * 8192), 16, 0, 0); } while (0)
; #define PG8_LDA(dst, b, h) do { _Pragma("unroll") for (int m = 0; m < 4; ++m) _Pragma("unroll") for (int k = 0; k < 2; ++k) dst[m][k] = *(const PG8_LAS bf16x8*)(lds + PG8_SA(b, h) + aoff + m * 2048 + k * 1024); } while (0)
; #define PG8_LDB(dst, b, h) do { _Pragma("unroll") for (int n = 0; n < 2; ++n) _Pragma("unroll") for (int k = 0; k < 2; ++k) dst[n][k] = *(const PG8_LAS bf16x8*)(lds + PG8_SB(b, h) + boff + n * 2048 + k * 1024); } while (0)
; #define PG8_MMA(ai, bj, At, Bt) do { __builtin_amdgcn_s_setprio(1); _Pragma("unroll") for (int m = 0; m < 4; ++m) _Pragma("unroll") for (int n = 0; n < 2; ++n) _Pragma("unroll") for (int k = 0; k < 2; ++k) \
;         acc[ai][bj][m][n] = __builtin_amdgcn_mfma_f32_16x16x32_bf16(Bt[n][k], At[m][k], acc[ai][bj][m][n], 0, 0, 0); __builtin_amdgcn_s_setprio(0); } while (0)
; #define PG8_WAIT_V(n) asm volatile("s_waitcnt vmcnt(" #n ")" ::: "memory")
; #define PG8_WAIT_L(n) asm volatile("s_waitcnt lgkmcnt(" #n ")" ::: "memory")
; #define PG8_BAR __builtin_amdgcn_s_barrier()
; #define PG8_SCHED __builtin_amdgcn_sched_barrier(0)
; template <class Epi, class Sched, bool ALIGN_EPI = false, bool SP2 = false>
; __device__ __forceinline__ void gemm_phase(PG8_LAS unsigned char* lds, const Gemm g, const Sched& S, const Epi& E) {
;     ...
;         for (int t = 0; t < nt; t += 2) {
;             const bool last = (t == nt - 2);
;             const char* a1 = cA + (size_t)(t + 1) * kstep;
;             const char* a2 = last ? nA : cA + (size_t)(t + 2) * kstep; const char* b2 = last ? nB : cB + (size_t)(t + 2) * kstep;
;     ...
;             PG8_LDB(B0, 1, 0); PG8_LDB(B1, 1, 1); PG8_SCHED; PG8_LDA(At, 1, 0); PG8_STAGE(PG8_SA(0, 1), a2 + hstep, voffA);
;             PG8_WAIT_V(8); PG8_WAIT_L(0); PG8_BAR; PG8_MMA(0, 0, At, B0); PG8_MMA(0, 1, At, B1); PG8_BAR; PG8_SCHED;
;             PG8_LDA(At, 1, 1); PG8_STAGE(PG8_SB(1, 0), b3, voffB); PG8_STAGE(PG8_SB(1, 1), b3 + hstep, voffB); PG8_STAGE(PG8_SA(1, 0), a3, voffA);
;             PG8_WAIT_V(8); PG8_WAIT_L(0); PG8_BAR; PG8_MMA(1, 0, At, B0); PG8_MMA(1, 1, At, B1); PG8_BAR; PG8_SCHED;
	s_add_i32 s49, 0, 0x18000
	v_add_u32_e32 v142, s49, v156
	s_add_i32 s50, 0, 0x1c000
	ds_read_b128 v[130:133], v142
	ds_read_b128 v[152:155], v142 offset:1024
	ds_read_b128 v[162:165], v142 offset:2048
	ds_read_b128 v[166:169], v142 offset:3072
	v_add_u32_e32 v142, s50, v156
	ds_read_b128 v[170:173], v142
	ds_read_b128 v[174:177], v142 offset:1024
	ds_read_b128 v[178:181], v142 offset:2048
	ds_read_b128 v[182:185], v142 offset:3072
	s_add_u32 s44, s44, 0x40000
	s_addc_u32 s45, s45, 0
	s_mov_b32 m0, s53
	ds_read_b128 v[186:189], v160 offset:32768
	ds_read_b128 v[190:193], v160 offset:33792
	ds_read_b128 v[198:201], v160 offset:34816
	ds_read_b128 v[202:205], v160 offset:35840
	ds_read_b128 v[206:209], v160 offset:36864
	ds_read_b128 v[210:213], v160 offset:37888
	ds_read_b128 v[214:217], v160 offset:38912
	ds_read_b128 v[218:221], v160 offset:39936
	global_load_lds_dwordx4 v134, s[44:45]
	s_mov_b32 m0, s54
	s_nop 0
	global_load_lds_dwordx4 v138, s[44:45]
	s_waitcnt vmcnt(8)
	s_waitcnt lgkmcnt(0)
	s_barrier
	s_setprio 1
	s_waitcnt lgkmcnt(0)
	v_mfma_f32_16x16x32_bf16 v[126:129], v[130:133], v[186:189], v[126:129]
	v_mfma_f32_16x16x32_bf16 v[122:125], v[162:165], v[186:189], v[122:125]
	v_mfma_f32_16x16x32_bf16 v[114:117], v[130:133], v[198:201], v[114:117]
	v_mfma_f32_16x16x32_bf16 v[106:109], v[162:165], v[198:201], v[106:109]
	v_mfma_f32_16x16x32_bf16 v[98:101], v[130:133], v[206:209], v[98:101]
	v_mfma_f32_16x16x32_bf16 v[90:93], v[162:165], v[206:209], v[90:93]
	v_mfma_f32_16x16x32_bf16 v[82:85], v[130:133], v[214:217], v[82:85]
	v_mfma_f32_16x16x32_bf16 v[74:77], v[162:165], v[214:217], v[74:77]
	v_mfma_f32_16x16x32_bf16 v[126:129], v[152:155], v[190:193], v[126:129]
	v_mfma_f32_16x16x32_bf16 v[122:125], v[166:169], v[190:193], v[122:125]
	v_mfma_f32_16x16x32_bf16 v[114:117], v[152:155], v[202:205], v[114:117]
	v_mfma_f32_16x16x32_bf16 v[106:109], v[166:169], v[202:205], v[106:109]
	v_mfma_f32_16x16x32_bf16 v[98:101], v[152:155], v[210:213], v[98:101]
	v_mfma_f32_16x16x32_bf16 v[90:93], v[166:169], v[210:213], v[90:93]
	v_mfma_f32_16x16x32_bf16 v[82:85], v[152:155], v[218:221], v[82:85]
	v_mfma_f32_16x16x32_bf16 v[74:77], v[166:169], v[218:221], v[74:77]
	s_setprio 0
	s_setprio 1
	v_mfma_f32_16x16x32_bf16 v[118:121], v[170:173], v[186:189], v[118:121]
	v_mfma_f32_16x16x32_bf16 v[110:113], v[178:181], v[186:189], v[110:113]
	v_mfma_f32_16x16x32_bf16 v[102:105], v[170:173], v[198:201], v[102:105]
	v_mfma_f32_16x16x32_bf16 v[94:97], v[178:181], v[198:201], v[94:97]
	v_mfma_f32_16x16x32_bf16 v[86:89], v[170:173], v[206:209], v[86:89]
	v_mfma_f32_16x16x32_bf16 v[78:81], v[178:181], v[206:209], v[78:81]
	v_mfma_f32_16x16x32_bf16 v[70:73], v[170:173], v[214:217], v[70:73]
	v_mfma_f32_16x16x32_bf16 v[66:69], v[178:181], v[214:217], v[66:69]
	v_mfma_f32_16x16x32_bf16 v[118:121], v[174:177], v[190:193], v[118:121]
	v_mfma_f32_16x16x32_bf16 v[110:113], v[182:185], v[190:193], v[110:113]
	v_mfma_f32_16x16x32_bf16 v[102:105], v[174:177], v[202:205], v[102:105]
	v_mfma_f32_16x16x32_bf16 v[94:97], v[182:185], v[202:205], v[94:97]
	v_mfma_f32_16x16x32_bf16 v[86:89], v[174:177], v[210:213], v[86:89]
	v_mfma_f32_16x16x32_bf16 v[78:81], v[182:185], v[210:213], v[78:81]
	v_mfma_f32_16x16x32_bf16 v[70:73], v[174:177], v[218:221], v[70:73]
	v_mfma_f32_16x16x32_bf16 v[66:69], v[182:185], v[218:221], v[66:69]
	s_setprio 0
	s_barrier
	s_add_i32 s44, s49, s17
	s_mov_b32 m0, s44
	ds_read_b128 v[186:189], v160 offset:49152
	ds_read_b128 v[190:193], v160 offset:50176
	ds_read_b128 v[198:201], v160 offset:51200
	ds_read_b128 v[202:205], v160 offset:52224
	ds_read_b128 v[206:209], v160 offset:53248
	ds_read_b128 v[210:213], v160 offset:54272
	ds_read_b128 v[214:217], v160 offset:55296
	ds_read_b128 v[218:221], v160 offset:56320
	global_load_lds_dwordx4 v136, s[98:99]
	s_add_i32 m0, s44, 0x2000
	s_add_u32 s40, s40, 0x40080
	s_addc_u32 s41, s41, 0
	s_add_i32 s44, s50, s17
	global_load_lds_dwordx4 v140, s[98:99]
	s_mov_b32 m0, s44
	s_nop 0
	global_load_lds_dwordx4 v136, s[40:41]
	s_add_i32 m0, s44, 0x2000
	s_nop 0
	global_load_lds_dwordx4 v140, s[40:41]
	s_mov_b32 m0, s55
	s_nop 0
	global_load_lds_dwordx4 v134, s[100:101]
	s_mov_b32 m0, s56
	s_nop 0
	global_load_lds_dwordx4 v138, s[100:101]
	s_waitcnt vmcnt(8)
	s_waitcnt lgkmcnt(0)
	s_barrier
	s_setprio 1
	s_waitcnt lgkmcnt(0)
	v_mfma_f32_16x16x32_bf16 v[62:65], v[130:133], v[186:189], v[62:65]
	v_mfma_f32_16x16x32_bf16 v[58:61], v[162:165], v[186:189], v[58:61]
	v_mfma_f32_16x16x32_bf16 v[50:53], v[130:133], v[198:201], v[50:53]
	v_mfma_f32_16x16x32_bf16 v[42:45], v[162:165], v[198:201], v[42:45]
	v_mfma_f32_16x16x32_bf16 v[34:37], v[130:133], v[206:209], v[34:37]
	v_mfma_f32_16x16x32_bf16 v[26:29], v[162:165], v[206:209], v[26:29]
	v_mfma_f32_16x16x32_bf16 v[18:21], v[130:133], v[214:217], v[18:21]
	v_mfma_f32_16x16x32_bf16 v[10:13], v[162:165], v[214:217], v[10:13]
	v_mfma_f32_16x16x32_bf16 v[62:65], v[152:155], v[190:193], v[62:65]
	v_mfma_f32_16x16x32_bf16 v[58:61], v[166:169], v[190:193], v[58:61]
	v_mfma_f32_16x16x32_bf16 v[50:53], v[152:155], v[202:205], v[50:53]
	v_mfma_f32_16x16x32_bf16 v[42:45], v[166:169], v[202:205], v[42:45]
	v_mfma_f32_16x16x32_bf16 v[34:37], v[152:155], v[210:213], v[34:37]
	v_mfma_f32_16x16x32_bf16 v[26:29], v[166:169], v[210:213], v[26:29]
	v_mfma_f32_16x16x32_bf16 v[18:21], v[152:155], v[218:221], v[18:21]
	v_mfma_f32_16x16x32_bf16 v[10:13], v[166:169], v[218:221], v[10:13]
	s_setprio 0
	s_setprio 1
	v_mfma_f32_16x16x32_bf16 v[54:57], v[170:173], v[186:189], v[54:57]
	v_mfma_f32_16x16x32_bf16 v[46:49], v[178:181], v[186:189], v[46:49]
	v_mfma_f32_16x16x32_bf16 v[38:41], v[170:173], v[198:201], v[38:41]
	v_mfma_f32_16x16x32_bf16 v[30:33], v[178:181], v[198:201], v[30:33]
	v_mfma_f32_16x16x32_bf16 v[22:25], v[170:173], v[206:209], v[22:25]
	v_mfma_f32_16x16x32_bf16 v[14:17], v[178:181], v[206:209], v[14:17]
	v_mfma_f32_16x16x32_bf16 v[6:9], v[170:173], v[214:217], v[6:9]
	v_mfma_f32_16x16x32_bf16 v[2:5], v[178:181], v[214:217], v[2:5]
	v_mfma_f32_16x16x32_bf16 v[54:57], v[174:177], v[190:193], v[54:57]
	v_mfma_f32_16x16x32_bf16 v[46:49], v[182:185], v[190:193], v[46:49]
	v_mfma_f32_16x16x32_bf16 v[38:41], v[174:177], v[202:205], v[38:41]
	v_mfma_f32_16x16x32_bf16 v[30:33], v[182:185], v[202:205], v[30:33]
	v_mfma_f32_16x16x32_bf16 v[22:25], v[174:177], v[210:213], v[22:25]
	v_mfma_f32_16x16x32_bf16 v[14:17], v[182:185], v[210:213], v[14:17]
	v_mfma_f32_16x16x32_bf16 v[6:9], v[174:177], v[218:221], v[6:9]
	v_mfma_f32_16x16x32_bf16 v[2:5], v[182:185], v[218:221], v[2:5]
	s_setprio 0
	s_barrier
	s_add_i32 s48, s48, 2
	s_add_u32 s38, s38, 0x100
	s_addc_u32 s39, s39, 0
	s_add_u32 s46, s46, 0x100
	s_addc_u32 s47, s47, 0
	s_cmp_gt_u32 s48, 13
	s_cbranch_scc0 .LBB0_142
	s_and_b64 vcc, exec, s[12:13]
	s_cbranch_vccz .LBB0_145
	s_barrier
